# scan step loop rewritten with row-paired state (fewer VALU), P6 epilogue loads hoisted, s_setprio 3 on scan waves
# speedup vs baseline: 1.0326x; 1.0326x over previous
.LBB0_472:
	s_setprio 0
	s_mov_b64 s[0:1], 0

.LBB0_478:
	s_or_b64 exec, exec, s[0:1]
	s_waitcnt lgkmcnt(0)
	s_barrier
	s_waitcnt vmcnt(6)
	ds_read_b32 v0, v41 offset:4
	s_movk_i32 s0, 0xff
	s_waitcnt lgkmcnt(0)
	v_cmp_lt_i32_e32 vcc, s0, v0
	v_readfirstlane_b32 s59, v0
	s_mov_b64 s[0:1], -1
	s_cbranch_vccnz .LBB0_473
	s_setprio 3
	s_lshl_b32 s0, s59, 6
	s_and_b32 s58, s0, 0x3c0
	s_barrier
	s_and_saveexec_b64 s[0:1], s[20:21]
	s_cbranch_execz .LBB0_481
	s_lshl_b32 s28, s58, 2
	v_lshl_add_u64 v[0:1], v[44:45], 0, s[28:29]
	global_load_dword v2, v[0:1], off
	v_lshl_add_u64 v[0:1], v[46:47], 0, s[28:29]
	global_load_dword v0, v[0:1], off
	s_waitcnt vmcnt(0)
	ds_write2st64_b32 v203, v2, v0 offset0:120 offset1:121
	v_lshl_add_u64 v[0:1], v[48:49], 0, s[28:29]
	global_load_dword v2, v[0:1], off
	v_lshl_add_u64 v[0:1], v[54:55], 0, s[28:29]
	global_load_dword v0, v[0:1], off
	s_waitcnt vmcnt(0)
	ds_write2st64_b32 v203, v2, v0 offset0:122 offset1:123
	v_lshl_add_u64 v[0:1], v[56:57], 0, s[28:29]
	global_load_dword v2, v[0:1], off
	v_lshl_add_u64 v[0:1], v[58:59], 0, s[28:29]
	global_load_dword v0, v[0:1], off
	s_waitcnt vmcnt(0)
	ds_write2st64_b32 v203, v2, v0 offset0:124 offset1:125
	v_lshl_add_u64 v[0:1], v[60:61], 0, s[28:29]
	global_load_dword v2, v[0:1], off
	v_lshl_add_u64 v[0:1], v[62:63], 0, s[28:29]
	global_load_dword v0, v[0:1], off
	s_waitcnt vmcnt(0)
	ds_write2st64_b32 v203, v2, v0 offset0:126 offset1:127

.LBB0_491:
	s_waitcnt lgkmcnt(1)
	v_pk_mul_f32 v[242:243], v[100:101], v[8:9] op_sel_hi:[1,0]
	v_pk_mul_f32 v[244:245], v[102:103], v[8:9] op_sel:[0,1] op_sel_hi:[1,1]
	v_pk_fma_f32 v[242:243], v[104:105], v[10:11], v[242:243] op_sel_hi:[1,0,1]
	v_pk_fma_f32 v[244:245], v[106:107], v[10:11], v[244:245] op_sel:[0,1,0] op_sel_hi:[1,1,1]
	ds_read_b128 v[210:213], v40
	ds_read_b128 v[214:217], v40 offset:16
	ds_read_b128 v[218:221], v40 offset:12288
	ds_read_b128 v[222:225], v40 offset:12304
	ds_read_b128 v[226:229], v40 offset:4096
	ds_read_b128 v[230:233], v40 offset:4112
	ds_read_b128 v[16:19], v40 offset:8448
	ds_read_b128 v[20:23], v40 offset:8464
	ds_read_b64 v[118:119], v209
	ds_read_b128 v[234:237], v40 offset:16384
	ds_read_b128 v[238:241], v40 offset:16400
	v_pk_fma_f32 v[242:243], v[108:109], v[12:13], v[242:243] op_sel_hi:[1,0,1]
	v_pk_fma_f32 v[244:245], v[110:111], v[12:13], v[244:245] op_sel:[0,1,0] op_sel_hi:[1,1,1]
	v_pk_fma_f32 v[242:243], v[112:113], v[14:15], v[242:243] op_sel_hi:[1,0,1]
	v_pk_fma_f32 v[244:245], v[114:115], v[14:15], v[244:245] op_sel:[0,1,0] op_sel_hi:[1,1,1]
	s_nop 0
	v_pk_add_f32 v[242:243], v[242:243], v[244:245]
	s_nop 1
	v_add_f32_dpp v242, v242, v242 quad_perm:[1,0,3,2] row_mask:0xf bank_mask:0xf bound_ctrl:1
	v_add_f32_dpp v243, v243, v243 quad_perm:[1,0,3,2] row_mask:0xf bank_mask:0xf bound_ctrl:1
	s_nop 0
	v_add_f32_dpp v242, v242, v242 quad_perm:[2,3,0,1] row_mask:0xf bank_mask:0xf bound_ctrl:1
	v_add_f32_dpp v243, v243, v243 quad_perm:[2,3,0,1] row_mask:0xf bank_mask:0xf bound_ctrl:1
	s_nop 0
	v_add_f32_dpp v242, v242, v242 row_half_mirror row_mask:0xf bank_mask:0xf bound_ctrl:1
	v_add_f32_dpp v243, v243, v243 row_half_mirror row_mask:0xf bank_mask:0xf bound_ctrl:1
	s_waitcnt lgkmcnt(6)
	v_pk_mul_f32 v[12:13], v[242:243], v[218:219] op_sel_hi:[1,0]
	v_pk_mul_f32 v[14:15], v[242:243], v[218:219] op_sel:[0,1] op_sel_hi:[1,1]
	v_pk_fma_f32 v[12:13], v[116:117], v[226:227], v[12:13] op_sel_hi:[1,0,1]
	v_pk_fma_f32 v[14:15], v[116:117], v[226:227], v[14:15] op_sel:[0,1,0] op_sel_hi:[1,1,1]
	v_pk_fma_f32 v[100:101], v[100:101], v[210:211], v[12:13] op_sel_hi:[1,0,1]
	v_pk_fma_f32 v[102:103], v[102:103], v[210:211], v[14:15] op_sel:[0,1,0] op_sel_hi:[1,1,1]
	v_pk_mul_f32 v[12:13], v[242:243], v[220:221] op_sel_hi:[1,0]
	v_pk_mul_f32 v[14:15], v[242:243], v[220:221] op_sel:[0,1] op_sel_hi:[1,1]
	v_pk_fma_f32 v[12:13], v[116:117], v[228:229], v[12:13] op_sel_hi:[1,0,1]
	v_pk_fma_f32 v[14:15], v[116:117], v[228:229], v[14:15] op_sel:[0,1,0] op_sel_hi:[1,1,1]
	v_pk_fma_f32 v[104:105], v[104:105], v[212:213], v[12:13] op_sel_hi:[1,0,1]
	v_pk_fma_f32 v[106:107], v[106:107], v[212:213], v[14:15] op_sel:[0,1,0] op_sel_hi:[1,1,1]
	s_waitcnt lgkmcnt(5)
	v_pk_mul_f32 v[12:13], v[242:243], v[222:223] op_sel_hi:[1,0]
	v_pk_mul_f32 v[14:15], v[242:243], v[222:223] op_sel:[0,1] op_sel_hi:[1,1]
	v_pk_fma_f32 v[12:13], v[116:117], v[230:231], v[12:13] op_sel_hi:[1,0,1]
	v_pk_fma_f32 v[14:15], v[116:117], v[230:231], v[14:15] op_sel:[0,1,0] op_sel_hi:[1,1,1]
	v_pk_fma_f32 v[108:109], v[108:109], v[214:215], v[12:13] op_sel_hi:[1,0,1]
	v_pk_fma_f32 v[110:111], v[110:111], v[214:215], v[14:15] op_sel:[0,1,0] op_sel_hi:[1,1,1]
	v_pk_mul_f32 v[12:13], v[242:243], v[224:225] op_sel_hi:[1,0]
	v_pk_mul_f32 v[14:15], v[242:243], v[224:225] op_sel:[0,1] op_sel_hi:[1,1]
	v_pk_fma_f32 v[12:13], v[116:117], v[232:233], v[12:13] op_sel_hi:[1,0,1]
	v_pk_fma_f32 v[14:15], v[116:117], v[232:233], v[14:15] op_sel:[0,1,0] op_sel_hi:[1,1,1]
	v_pk_fma_f32 v[112:113], v[112:113], v[216:217], v[12:13] op_sel_hi:[1,0,1]
	v_pk_fma_f32 v[114:115], v[114:115], v[216:217], v[14:15] op_sel:[0,1,0] op_sel_hi:[1,1,1]
	s_waitcnt lgkmcnt(0)
	v_pk_mul_f32 v[8:9], v[100:101], v[234:235] op_sel_hi:[1,0]
	v_pk_mul_f32 v[10:11], v[102:103], v[234:235] op_sel:[0,1] op_sel_hi:[1,1]
	v_pk_fma_f32 v[8:9], v[104:105], v[236:237], v[8:9] op_sel_hi:[1,0,1]
	v_pk_fma_f32 v[10:11], v[106:107], v[236:237], v[10:11] op_sel:[0,1,0] op_sel_hi:[1,1,1]
	v_pk_fma_f32 v[8:9], v[108:109], v[238:239], v[8:9] op_sel_hi:[1,0,1]
	v_pk_fma_f32 v[10:11], v[110:111], v[238:239], v[10:11] op_sel:[0,1,0] op_sel_hi:[1,1,1]
	v_pk_fma_f32 v[8:9], v[112:113], v[240:241], v[8:9] op_sel_hi:[1,0,1]
	v_pk_fma_f32 v[10:11], v[114:115], v[240:241], v[10:11] op_sel:[0,1,0] op_sel_hi:[1,1,1]
	s_nop 0
	v_pk_add_f32 v[8:9], v[8:9], v[10:11]
	s_nop 1
	v_add_f32_dpp v8, v8, v8 quad_perm:[1,0,3,2] row_mask:0xf bank_mask:0xf bound_ctrl:1
	v_add_f32_dpp v9, v9, v9 quad_perm:[1,0,3,2] row_mask:0xf bank_mask:0xf bound_ctrl:1
	s_nop 0
	v_add_f32_dpp v8, v8, v8 quad_perm:[2,3,0,1] row_mask:0xf bank_mask:0xf bound_ctrl:1
	v_add_f32_dpp v9, v9, v9 quad_perm:[2,3,0,1] row_mask:0xf bank_mask:0xf bound_ctrl:1
	s_nop 0
	v_add_f32_dpp v8, v8, v8 row_half_mirror row_mask:0xf bank_mask:0xf bound_ctrl:1
	v_add_f32_dpp v9, v9, v9 row_half_mirror row_mask:0xf bank_mask:0xf bound_ctrl:1
	s_and_saveexec_b64 s[60:61], s[26:27]
	ds_write_b64 v209, v[8:9] offset:3840
	s_or_b64 exec, exec, s[60:61]
	v_pk_mul_f32 v[242:243], v[100:101], v[16:17] op_sel_hi:[1,0]
	v_pk_mul_f32 v[244:245], v[102:103], v[16:17] op_sel:[0,1] op_sel_hi:[1,1]
	v_pk_fma_f32 v[242:243], v[104:105], v[18:19], v[242:243] op_sel_hi:[1,0,1]
	v_pk_fma_f32 v[244:245], v[106:107], v[18:19], v[244:245] op_sel:[0,1,0] op_sel_hi:[1,1,1]
	ds_read_b128 v[210:213], v40 offset:256
	ds_read_b128 v[214:217], v40 offset:272
	ds_read_b128 v[218:221], v40 offset:12544
	ds_read_b128 v[222:225], v40 offset:12560
	ds_read_b128 v[226:229], v40 offset:4352
	ds_read_b128 v[230:233], v40 offset:4368
	s_add_i32 s60, s63, 18
	s_cmp_lg_u32 s63, -2
	s_cselect_b32 s60, s60, 15
	s_lshl_b32 s60, s60, 8
	v_pk_fma_f32 v[242:243], v[108:109], v[20:21], v[242:243] op_sel_hi:[1,0,1]
	v_pk_fma_f32 v[244:245], v[110:111], v[20:21], v[244:245] op_sel:[0,1,0] op_sel_hi:[1,1,1]
	v_pk_fma_f32 v[242:243], v[112:113], v[22:23], v[242:243] op_sel_hi:[1,0,1]
	v_pk_fma_f32 v[244:245], v[114:115], v[22:23], v[244:245] op_sel:[0,1,0] op_sel_hi:[1,1,1]
	s_nop 0
	v_pk_add_f32 v[242:243], v[242:243], v[244:245]
	s_nop 1
	v_add_f32_dpp v242, v242, v242 quad_perm:[1,0,3,2] row_mask:0xf bank_mask:0xf bound_ctrl:1
	v_add_f32_dpp v243, v243, v243 quad_perm:[1,0,3,2] row_mask:0xf bank_mask:0xf bound_ctrl:1
	s_nop 0
	v_add_f32_dpp v242, v242, v242 quad_perm:[2,3,0,1] row_mask:0xf bank_mask:0xf bound_ctrl:1
	v_add_f32_dpp v243, v243, v243 quad_perm:[2,3,0,1] row_mask:0xf bank_mask:0xf bound_ctrl:1
	s_nop 0
	v_add_f32_dpp v242, v242, v242 row_half_mirror row_mask:0xf bank_mask:0xf bound_ctrl:1
	v_add_f32_dpp v243, v243, v243 row_half_mirror row_mask:0xf bank_mask:0xf bound_ctrl:1
	v_or_b32_e32 v12, s60, v177
	v_add_u32_e32 v116, s60, v193
	ds_read_b128 v[8:11], v12 offset:8192
	ds_read_b128 v[12:15], v12 offset:8208
	ds_read_b64 v[116:117], v116 offset:20480
	ds_read_b128 v[234:237], v40 offset:16640
	ds_read_b128 v[238:241], v40 offset:16656
	s_waitcnt lgkmcnt(6)
	v_pk_mul_f32 v[20:21], v[242:243], v[218:219] op_sel_hi:[1,0]
	v_pk_mul_f32 v[22:23], v[242:243], v[218:219] op_sel:[0,1] op_sel_hi:[1,1]
	v_pk_fma_f32 v[20:21], v[118:119], v[226:227], v[20:21] op_sel_hi:[1,0,1]
	v_pk_fma_f32 v[22:23], v[118:119], v[226:227], v[22:23] op_sel:[0,1,0] op_sel_hi:[1,1,1]
	v_pk_fma_f32 v[100:101], v[100:101], v[210:211], v[20:21] op_sel_hi:[1,0,1]
	v_pk_fma_f32 v[102:103], v[102:103], v[210:211], v[22:23] op_sel:[0,1,0] op_sel_hi:[1,1,1]
	v_pk_mul_f32 v[20:21], v[242:243], v[220:221] op_sel_hi:[1,0]
	v_pk_mul_f32 v[22:23], v[242:243], v[220:221] op_sel:[0,1] op_sel_hi:[1,1]
	v_pk_fma_f32 v[20:21], v[118:119], v[228:229], v[20:21] op_sel_hi:[1,0,1]
	v_pk_fma_f32 v[22:23], v[118:119], v[228:229], v[22:23] op_sel:[0,1,0] op_sel_hi:[1,1,1]
	v_pk_fma_f32 v[104:105], v[104:105], v[212:213], v[20:21] op_sel_hi:[1,0,1]
	v_pk_fma_f32 v[106:107], v[106:107], v[212:213], v[22:23] op_sel:[0,1,0] op_sel_hi:[1,1,1]
	s_waitcnt lgkmcnt(5)
	v_pk_mul_f32 v[20:21], v[242:243], v[222:223] op_sel_hi:[1,0]
	v_pk_mul_f32 v[22:23], v[242:243], v[222:223] op_sel:[0,1] op_sel_hi:[1,1]
	v_pk_fma_f32 v[20:21], v[118:119], v[230:231], v[20:21] op_sel_hi:[1,0,1]
	v_pk_fma_f32 v[22:23], v[118:119], v[230:231], v[22:23] op_sel:[0,1,0] op_sel_hi:[1,1,1]
	v_pk_fma_f32 v[108:109], v[108:109], v[214:215], v[20:21] op_sel_hi:[1,0,1]
	v_pk_fma_f32 v[110:111], v[110:111], v[214:215], v[22:23] op_sel:[0,1,0] op_sel_hi:[1,1,1]
	v_pk_mul_f32 v[20:21], v[242:243], v[224:225] op_sel_hi:[1,0]
	v_pk_mul_f32 v[22:23], v[242:243], v[224:225] op_sel:[0,1] op_sel_hi:[1,1]
	v_pk_fma_f32 v[20:21], v[118:119], v[232:233], v[20:21] op_sel_hi:[1,0,1]
	v_pk_fma_f32 v[22:23], v[118:119], v[232:233], v[22:23] op_sel:[0,1,0] op_sel_hi:[1,1,1]
	v_pk_fma_f32 v[112:113], v[112:113], v[216:217], v[20:21] op_sel_hi:[1,0,1]
	v_pk_fma_f32 v[114:115], v[114:115], v[216:217], v[22:23] op_sel:[0,1,0] op_sel_hi:[1,1,1]
	s_waitcnt lgkmcnt(0)
	v_pk_mul_f32 v[16:17], v[100:101], v[234:235] op_sel_hi:[1,0]
	v_pk_mul_f32 v[18:19], v[102:103], v[234:235] op_sel:[0,1] op_sel_hi:[1,1]
	v_pk_fma_f32 v[16:17], v[104:105], v[236:237], v[16:17] op_sel_hi:[1,0,1]
	v_pk_fma_f32 v[18:19], v[106:107], v[236:237], v[18:19] op_sel:[0,1,0] op_sel_hi:[1,1,1]
	v_pk_fma_f32 v[16:17], v[108:109], v[238:239], v[16:17] op_sel_hi:[1,0,1]
	v_pk_fma_f32 v[18:19], v[110:111], v[238:239], v[18:19] op_sel:[0,1,0] op_sel_hi:[1,1,1]
	v_pk_fma_f32 v[16:17], v[112:113], v[240:241], v[16:17] op_sel_hi:[1,0,1]
	v_pk_fma_f32 v[18:19], v[114:115], v[240:241], v[18:19] op_sel:[0,1,0] op_sel_hi:[1,1,1]
	s_nop 0
	v_pk_add_f32 v[16:17], v[16:17], v[18:19]
	s_nop 1
	v_add_f32_dpp v16, v16, v16 quad_perm:[1,0,3,2] row_mask:0xf bank_mask:0xf bound_ctrl:1
	v_add_f32_dpp v17, v17, v17 quad_perm:[1,0,3,2] row_mask:0xf bank_mask:0xf bound_ctrl:1
	s_nop 0
	v_add_f32_dpp v16, v16, v16 quad_perm:[2,3,0,1] row_mask:0xf bank_mask:0xf bound_ctrl:1
	v_add_f32_dpp v17, v17, v17 quad_perm:[2,3,0,1] row_mask:0xf bank_mask:0xf bound_ctrl:1
	s_nop 0
	v_add_f32_dpp v16, v16, v16 row_half_mirror row_mask:0xf bank_mask:0xf bound_ctrl:1
	v_add_f32_dpp v17, v17, v17 row_half_mirror row_mask:0xf bank_mask:0xf bound_ctrl:1
	s_and_saveexec_b64 s[60:61], s[26:27]
	ds_write_b64 v209, v[16:17] offset:4096
	s_or_b64 exec, exec, s[60:61]
	s_add_i32 s63, s63, 2
	v_add_u32_e32 v209, 0x200, v209
	v_add_u32_e32 v40, 0x200, v40
	s_cmp_eq_u32 s63, 0
	s_cbranch_scc0 .LBB0_491
	s_branch .LBB0_484

.LBB0_767:
	v_add_u32_e32 v94, s30, v106
	v_or_b32_e32 v96, s34, v109
	v_readlane_b32 s90, v248, 54
	v_readlane_b32 s91, v248, 55
	v_ashrrev_i32_e32 v95, 11, v94
	v_ashrrev_i32_e32 v97, 31, v96
	v_readlane_b32 s36, v247, 13
	v_readlane_b32 s37, v247, 14
	v_mul_i32_i24_e32 v98, 0x1800, v95
	v_lshlrev_b64 v[96:97], 2, v[96:97]
	v_readlane_b32 s48, v248, 5
	v_readlane_b32 s49, v248, 6
	v_ashrrev_i32_e32 v99, 31, v98
	v_ashrrev_i32_e32 v95, 31, v94
	v_lshl_add_u64 v[98:99], v[98:99], 2, s[90:91]
	v_lshlrev_b64 v[100:101], 12, v[94:95]
	v_lshl_add_u64 v[98:99], v[98:99], 0, v[96:97]
	v_lshl_add_u64 v[100:101], v[100:101], 0, v[96:97]
	v_lshl_add_u64 v[98:99], v[98:99], 0, s[28:29]
	s_mov_b64 s[50:51], 0x10000
	v_lshl_add_u64 v[102:103], s[36:37], 0, v[100:101]
	global_load_dwordx4 v[140:143], v[98:99], off
	global_load_dwordx4 v[144:147], v[98:99], off offset:16
	global_load_dwordx4 v[148:151], v[98:99], off offset:32
	global_load_dwordx4 v[178:181], v[98:99], off offset:48
	global_load_dwordx4 v[182:185], v[102:103], off
	global_load_dwordx4 v[186:189], v[102:103], off offset:16
	global_load_dwordx4 v[190:193], v[102:103], off offset:32
	global_load_dwordx4 v[194:197], v[102:103], off offset:48
	v_lshl_add_u64 v[162:163], v[102:103], 0, s[50:51]
	global_load_dwordx4 v[198:201], v[162:163], off
	global_load_dwordx4 v[202:205], v[162:163], off offset:16
	global_load_dwordx4 v[206:209], v[162:163], off offset:32
	global_load_dwordx4 v[210:213], v[162:163], off offset:48
	v_lshl_add_u64 v[164:165], v[162:163], 0, s[50:51]
	global_load_dwordx4 v[214:217], v[164:165], off
	global_load_dwordx4 v[218:221], v[164:165], off offset:16
	global_load_dwordx4 v[222:225], v[164:165], off offset:32
	global_load_dwordx4 v[226:229], v[164:165], off offset:48
	v_lshl_add_u64 v[166:167], v[164:165], 0, s[50:51]
	global_load_dwordx4 v[230:233], v[166:167], off
	global_load_dwordx4 v[234:237], v[166:167], off offset:16
	global_load_dwordx4 v[238:241], v[166:167], off offset:32
	global_load_dwordx4 v[242:245], v[166:167], off offset:48
	v_lshl_add_u64 v[104:105], s[48:49], 0, v[100:101]
	v_lshl_add_u64 v[168:169], v[104:105], 0, s[50:51]
	v_lshl_add_u64 v[170:171], v[168:169], 0, s[50:51]
	v_lshl_add_u64 v[152:153], v[170:171], 0, s[50:51]
	s_waitcnt vmcnt(15)
	v_pk_fma_f32 v[182:183], v[60:61], v[140:141], v[182:183]
	v_pk_fma_f32 v[184:185], v[62:63], v[142:143], v[184:185]
	global_store_dwordx4 v[104:105], v[182:185], off
	s_waitcnt vmcnt(15)
	v_pk_fma_f32 v[186:187], v[56:57], v[144:145], v[186:187]
	v_pk_fma_f32 v[188:189], v[58:59], v[146:147], v[188:189]
	global_store_dwordx4 v[104:105], v[186:189], off offset:16
	s_waitcnt vmcnt(15)
	v_pk_fma_f32 v[190:191], v[52:53], v[148:149], v[190:191]
	v_pk_fma_f32 v[192:193], v[54:55], v[150:151], v[192:193]
	global_store_dwordx4 v[104:105], v[190:193], off offset:32
	s_waitcnt vmcnt(15)
	v_pk_fma_f32 v[194:195], v[48:49], v[178:179], v[194:195]
	v_pk_fma_f32 v[196:197], v[50:51], v[180:181], v[196:197]
	global_store_dwordx4 v[104:105], v[194:197], off offset:48
	s_waitcnt vmcnt(15)
	v_pk_fma_f32 v[198:199], v[44:45], v[140:141], v[198:199]
	v_pk_fma_f32 v[200:201], v[46:47], v[142:143], v[200:201]
	global_store_dwordx4 v[168:169], v[198:201], off
	s_waitcnt vmcnt(15)
	v_pk_fma_f32 v[202:203], v[40:41], v[144:145], v[202:203]
	v_pk_fma_f32 v[204:205], v[42:43], v[146:147], v[204:205]
	global_store_dwordx4 v[168:169], v[202:205], off offset:16
	s_waitcnt vmcnt(15)
	v_pk_fma_f32 v[206:207], v[36:37], v[148:149], v[206:207]
	v_pk_fma_f32 v[208:209], v[38:39], v[150:151], v[208:209]
	global_store_dwordx4 v[168:169], v[206:209], off offset:32
	s_waitcnt vmcnt(15)
	v_pk_fma_f32 v[210:211], v[32:33], v[178:179], v[210:211]
	v_pk_fma_f32 v[212:213], v[34:35], v[180:181], v[212:213]
	global_store_dwordx4 v[168:169], v[210:213], off offset:48
	s_waitcnt vmcnt(15)
	v_pk_fma_f32 v[214:215], v[28:29], v[140:141], v[214:215]
	v_pk_fma_f32 v[216:217], v[30:31], v[142:143], v[216:217]
	global_store_dwordx4 v[170:171], v[214:217], off
	s_waitcnt vmcnt(15)
	v_pk_fma_f32 v[218:219], v[24:25], v[144:145], v[218:219]
	v_pk_fma_f32 v[220:221], v[26:27], v[146:147], v[220:221]
	global_store_dwordx4 v[170:171], v[218:221], off offset:16
	s_waitcnt vmcnt(15)
	v_pk_fma_f32 v[222:223], v[20:21], v[148:149], v[222:223]
	v_pk_fma_f32 v[224:225], v[22:23], v[150:151], v[224:225]
	global_store_dwordx4 v[170:171], v[222:225], off offset:32
	s_waitcnt vmcnt(15)
	v_pk_fma_f32 v[226:227], v[12:13], v[178:179], v[226:227]
	v_pk_fma_f32 v[228:229], v[14:15], v[180:181], v[228:229]
	global_store_dwordx4 v[170:171], v[226:229], off offset:48
	s_waitcnt vmcnt(15)
	v_pk_fma_f32 v[230:231], v[4:5], v[140:141], v[230:231]
	v_pk_fma_f32 v[232:233], v[6:7], v[142:143], v[232:233]
	global_store_dwordx4 v[152:153], v[230:233], off
	s_waitcnt vmcnt(15)
	v_pk_fma_f32 v[234:235], v[0:1], v[144:145], v[234:235]
	v_pk_fma_f32 v[236:237], v[2:3], v[146:147], v[236:237]
	global_store_dwordx4 v[152:153], v[234:237], off offset:16
	s_waitcnt vmcnt(15)
	v_pk_fma_f32 v[238:239], v[16:17], v[148:149], v[238:239]
	v_pk_fma_f32 v[240:241], v[18:19], v[150:151], v[240:241]
	global_store_dwordx4 v[152:153], v[238:241], off offset:32
	s_waitcnt vmcnt(15)
	v_pk_fma_f32 v[242:243], v[8:9], v[178:179], v[242:243]
	v_pk_fma_f32 v[244:245], v[10:11], v[180:181], v[244:245]
	global_store_dwordx4 v[152:153], v[242:245], off offset:48
	s_add_i32 s33, s33, s59
	s_add_i32 s41, s41, s42
	s_add_i32 s43, s43, s44
	s_cmpk_lt_i32 s33, 0x100
	s_cbranch_scc0 .LBB0_772
